# grid barrier before out-proj/MLP1/MLP2 phases releases per XCD without the cross-XCD rendezvous (their inputs are produced on the same XCD), guarded by a runtime check that every blockIdx&7 group sits
# speedup vs baseline: 1.0167x; 1.0167x over previous
; #define LAS __attribute__((address_space(3)))
; DEVI unsigned xb_add(unsigned* p, unsigned v) { return __hip_atomic_fetch_add(p, v, __ATOMIC_RELAXED, __HIP_MEMORY_SCOPE_AGENT); }
; DEVI unsigned xb_xcc_id() { return (unsigned)__builtin_amdgcn_s_getreg((3 << 11) | 20) & 0xFu; }
; DEVI XcdBarrier xcd_barrier_post(unsigned* bar, volatile LAS unsigned* st) {
;   XcdBarrier b; b.bar = bar; b.x = xb_xcc_id(); b.st = st;
;   if (threadIdx.x == 0) (void)xb_add(&bar[XB_XCNT(b.x)], 1u);
;   return b;
; }
; __global__ void __launch_bounds__(512, 2) fwd_mega(Params p, int ph_lo, int ph_hi, int coop) {
;     ...
;   if (coop) {
;     if (threadIdx.x == 0) xb_words = make_uint4(0u, 0u, 0u, 0u);
;     __syncthreads();
;     xb = xcd_barrier_post((unsigned*)(p.ws + OFF_BAR), (volatile LAS unsigned*)&xb_words);
;   }
_Z8fwd_mega6Paramsiii:
	s_load_dwordx8 s[88:95], s[0:1], 0xc0
	v_writelane_b32 v244, s2, 0
	s_waitcnt lgkmcnt(0)
	s_cmp_lg_u32 s94, 0
	s_cselect_b64 s[2:3], -1, 0
	v_writelane_b32 v244, s2, 1
	s_cmp_eq_u32 s94, 0
	s_nop 0
	v_writelane_b32 v244, s3, 2
	s_cbranch_scc1 .LBB0_7
	v_and_b32_e32 v1, 0x3ff, v0
	v_cmp_eq_u32_e32 vcc, 0, v1
	s_and_saveexec_b64 s[2:3], vcc
	v_mov_b32_e32 v2, 0
	v_mov_b32_e32 v3, v2
	v_mov_b32_e32 v4, v2
	v_mov_b32_e32 v5, v2
	ds_write_b128 v2, v[2:5] offset:3072
	s_or_b64 exec, exec, s[2:3]
	s_add_u32 s2, s90, 0xf588000
	s_addc_u32 s3, s91, 0
	v_writelane_b32 v244, s2, 51
	s_waitcnt lgkmcnt(0)
	s_barrier
	v_writelane_b32 v244, s3, 52
	s_getreg_b32 s2, hwreg(HW_REG_XCC_ID, 0, 4)
	s_and_b32 s8, s2, 15
	s_and_saveexec_b64 s[2:3], vcc
	s_cbranch_execz .LBB0_6
	s_mov_b64 s[4:5], exec
	v_mbcnt_lo_u32_b32 v1, s4, 0
	v_mbcnt_hi_u32_b32 v1, s5, v1
	v_cmp_eq_u32_e32 vcc, 0, v1
	s_and_b64 s[6:7], exec, vcc
	s_mov_b64 exec, s[6:7]
	s_cbranch_execz .LBB0_6
	s_bcnt1_i32_b64 s4, s[4:5]
	s_lshl_b32 s6, s8, 8
	v_mov_b32_e32 v2, s4
	v_readlane_b32 s4, v244, 51
	v_mov_b32_e32 v1, s6
	v_readlane_b32 s5, v244, 52
	s_nop 4
	global_atomic_add v1, v2, s[4:5] offset:1024
	v_readlane_b32 s6, v244, 0
	s_and_b32 s6, s6, 7
	s_lshl_b32 s6, s6, 2
	s_add_i32 s6, s6, 0x3600
	s_lshl_b32 s7, 1, s8
	v_mov_b32_e32 v3, s7
	v_mov_b32_e32 v4, s6
	global_atomic_or v4, v3, s[4:5]

; DEVI void xcd_barrier(const XcdBarrier& b) {
;   asm volatile("s_waitcnt vmcnt(0)" ::: "memory");
;   __syncthreads();
;   if (threadIdx.x == 0) {
;     unsigned* bar = b.bar;
;     __builtin_amdgcn_s_waitcnt(0);
;     unsigned nloc = b.st[0], nx = b.st[1];
;     if (nloc == 0u) { xcd_barrier_complete(bar, b.x, nloc, nx); b.st[0] = nloc; b.st[1] = nx; }
.LBB0_930:
	s_waitcnt vmcnt(0) expcnt(0) lgkmcnt(0)
	v_mov_b32_e32 v245, 0x3600
	global_load_dwordx4 v[246:249], v245, s[28:29] sc1
	global_load_dwordx4 v[250:253], v245, s[28:29] offset:16 sc1
	ds_read_b32 v3, v1 offset:3072
	ds_read_b32 v2, v1 offset:3076
	s_waitcnt lgkmcnt(1)
	v_cmp_ne_u32_e32 vcc, 0, v3
	s_cbranch_vccnz .LBB0_945
	v_readlane_b32 s36, v244, 57
	v_readlane_b32 s37, v244, 58
	s_load_dwordx2 s[26:27], s[36:37], 0x0
	s_load_dword s20, s[36:37], 0x8
	s_waitcnt lgkmcnt(0)
	s_mul_i32 s23, s27, s26
	s_mul_i32 s20, s23, s20
	s_mov_b32 s23, 1
	s_branch .LBB0_933

; DEVI unsigned xb_ld(unsigned* p) { return __hip_atomic_load(p, __ATOMIC_RELAXED, __HIP_MEMORY_SCOPE_AGENT); }
; DEVI unsigned xb_add(unsigned* p, unsigned v) { return __hip_atomic_fetch_add(p, v, __ATOMIC_RELAXED, __HIP_MEMORY_SCOPE_AGENT); }
; #define XB_SPIN(cond, bar) do { unsigned _sp = 0; while (cond) { __builtin_amdgcn_s_sleep(1); \
;     if ((++_sp & 255u) == 0u) { if (xb_ld(&(bar)[XB_TMO])) break; if (_sp > XB_SPIN_CAP) { atomicAdd(&(bar)[XB_TMO], 1u); break; } } } } while (0)
; DEVI void xcd_barrier(const XcdBarrier& b) {
;     ...
;     const unsigned old = xb_add(&bar[XB_XSUB(b.x)], 1u);
;     const unsigned gen = old / nloc;
;     if (old + 1u == (gen + 1u) * nloc) {
;       __builtin_amdgcn_fence(__ATOMIC_RELEASE, "agent");
;       asm volatile("s_waitcnt vmcnt(0)" ::: "memory");
;       const unsigned og = xb_add(&bar[XB_TOP], 1u);
;       const unsigned tg = og / nx;
;       if (og + 1u == (tg + 1u) * nx) xb_add(&bar[XB_TOPGEN], 1u);
;       else XB_SPIN(xb_ld(&bar[XB_TOPGEN]) == tg, bar);
.LBB0_962:
	s_and_b32 s20, s92, 7
	s_cmp_ge_u32 s20, 5
	s_cbranch_scc0 .Lxb_global
	v_readfirstlane_b32 s20, v246
	s_bcnt1_i32_b32 s20, s20
	s_cmp_lg_u32 s20, 1
	s_cbranch_scc1 .Lxb_global
	v_readfirstlane_b32 s20, v247
	s_bcnt1_i32_b32 s20, s20
	s_cmp_lg_u32 s20, 1
	s_cbranch_scc1 .Lxb_global
	v_readfirstlane_b32 s20, v248
	s_bcnt1_i32_b32 s20, s20
	s_cmp_lg_u32 s20, 1
	s_cbranch_scc1 .Lxb_global
	v_readfirstlane_b32 s20, v249
	s_bcnt1_i32_b32 s20, s20
	s_cmp_lg_u32 s20, 1
	s_cbranch_scc1 .Lxb_global
	v_readfirstlane_b32 s20, v250
	s_bcnt1_i32_b32 s20, s20
	s_cmp_lg_u32 s20, 1
	s_cbranch_scc1 .Lxb_global
	v_readfirstlane_b32 s20, v251
	s_bcnt1_i32_b32 s20, s20
	s_cmp_lg_u32 s20, 1
	s_cbranch_scc1 .Lxb_global
	v_readfirstlane_b32 s20, v252
	s_bcnt1_i32_b32 s20, s20
	s_cmp_lg_u32 s20, 1
	s_cbranch_scc1 .Lxb_global
	v_readfirstlane_b32 s20, v253
	s_bcnt1_i32_b32 s20, s20
	s_cmp_lg_u32 s20, 1
	s_cbranch_scc1 .Lxb_global
	s_branch .Lxb_local_leader

; DEVI unsigned xb_add(unsigned* p, unsigned v) { return __hip_atomic_fetch_add(p, v, __ATOMIC_RELAXED, __HIP_MEMORY_SCOPE_AGENT); }
; DEVI void xcd_barrier(const XcdBarrier& b) {
;     ...
;       __builtin_amdgcn_fence(__ATOMIC_ACQUIRE, "agent");
;       xb_add(&bar[XB_XGEN(b.x)], 1u);
;       asm volatile("s_waitcnt vmcnt(0)" ::: "memory");
.Lxb_local_leader:
	s_mov_b64 s[36:37], exec
	s_branch .LBB0_978
